# up GEMM: next tile's first A half-slab is staged before the C stores and the first K iteration after an epilogue is peeled with vmcnt(22), so the tile's 16 stores drain behind seven MFMA phases instea
# baseline (speedup 1.0000x reference)
.LBB0_173:
	v_lshrrev_b32_e32 v17, 1, v158
	v_and_b32_e32 v17, 24, v17
	v_and_b32_e32 v16, 15, v158
	v_lshlrev_b32_e32 v18, 1, v17
	v_lshl_or_b32 v140, s10, 6, v16
	v_lshl_or_b32 v16, v16, 6, v18
	v_lshlrev_b32_e32 v18, 2, v158
	s_sext_i32_i16 s50, s8
	s_lshl_b32 s8, s10, 13
	v_and_b32_e32 v18, 32, v18
	v_bitop3_b32 v19, v16, s8, v18 bitop3:0xde
	s_lshl_b32 s8, s9, 5
	s_and_b32 s10, s8, 0x60
	s_add_i32 m0, s3, 0x18000
	v_lshl_add_u64 v[8:9], v[8:9], 0, s[20:21]
	s_lshl_b32 s8, s10, 7
	s_waitcnt vmcnt(4)
	s_barrier
	global_load_lds_dwordx4 v[8:9], off
	v_lshl_add_u64 v[6:7], v[6:7], 0, s[20:21]
	s_add_i32 m0, s3, 0x1a000
	s_add_i32 s42, s3, 0x8000
	s_add_i32 s43, s3, 0xa000
	v_bitop3_b32 v141, s8, v16, v18 bitop3:0xf6
	global_load_lds_dwordx4 v[6:7], off
	v_lshl_add_u64 v[4:5], v[4:5], 0, s[20:21]
	s_mov_b32 m0, s42
	s_add_u32 s8, s18, 0x40080
	global_load_lds_dwordx4 v[4:5], off
	v_lshl_add_u64 v[2:3], v[2:3], 0, s[20:21]
	s_mov_b32 m0, s43
	s_addc_u32 s9, s19, 0
	global_load_lds_dwordx4 v[2:3], off
	s_add_i32 m0, s3, 0x1c000
	v_lshl_add_u64 v[2:3], s[8:9], 0, v[0:1]
	global_load_lds_dwordx4 v[2:3], off
	v_lshl_add_u64 v[2:3], s[8:9], 0, v[130:131]
	s_add_i32 m0, s3, 0x1e000
	s_ashr_i32 s48, s56, 31
	global_load_lds_dwordx4 v[2:3], off
	v_lshlrev_b32_e32 v2, 14, v10
	v_and_b32_e32 v2, 0xffff8000, v2
	v_lshl_add_u32 v2, v11, 11, v2
	v_and_b32_e32 v3, 1, v10
	v_lshl_or_b32 v2, v3, 6, v2
	v_lshl_add_u32 v136, v12, 1, v2
	v_lshlrev_b32_e32 v2, 14, v14
	v_and_b32_e32 v2, 0xffff8000, v2
	s_waitcnt vmcnt(6)
	v_lshl_add_u32 v2, v13, 11, v2
	v_and_b32_e32 v3, 1, v14
	v_lshl_or_b32 v2, v3, 6, v2
	v_or_b32_e32 v142, s10, v17
	v_mov_b32_e32 v137, v1
	v_lshl_add_u32 v138, v15, 1, v2
	v_mov_b32_e32 v139, v1
	s_mov_b32 s49, 0
	v_add_u32_e32 v143, 0, v19
	s_barrier
	s_mov_b32 s100, 0

.LBB0_176:
	v_mov_b64_e32 v[2:3], s[76:77]
	s_ashr_i32 s11, s10, 31
	v_cmp_lt_i64_e32 vcc, s[12:13], v[2:3]
	s_lshl_b64 s[12:13], s[10:11], 19
	s_add_u32 s12, s44, s12
	s_addc_u32 s13, s45, s13
	s_and_b64 s[14:15], vcc, exec
	s_cselect_b32 s11, s13, s23
	s_cselect_b32 s51, s12, s22
	s_ashr_i32 s9, s8, 31
	s_lshl_b64 s[14:15], s[8:9], 19
	s_add_u32 s14, s27, s14
	s_addc_u32 s15, s28, s15
	s_and_b64 s[24:25], vcc, exec
	s_cselect_b32 s9, s15, s19
	s_cselect_b32 s52, s14, s18
	s_add_u32 s53, s18, 0x100
	s_addc_u32 s54, s19, 0
	s_add_u32 s18, s22, 0x40080
	v_mov_b32_e32 v2, 0
	s_addc_u32 s19, s23, 0
	s_mov_b32 s55, -2
	v_mov_b32_e32 v3, v2
	v_mov_b32_e32 v4, v2
	v_mov_b32_e32 v5, v2
	v_mov_b32_e32 v6, v2
	v_mov_b32_e32 v7, v2
	v_mov_b32_e32 v8, v2
	v_mov_b32_e32 v9, v2
	v_mov_b32_e32 v10, v2
	v_mov_b32_e32 v11, v2
	v_mov_b32_e32 v12, v2
	v_mov_b32_e32 v13, v2
	v_mov_b32_e32 v14, v2
	v_mov_b32_e32 v15, v2
	v_mov_b32_e32 v16, v2
	v_mov_b32_e32 v17, v2
	v_mov_b32_e32 v26, v2
	v_mov_b32_e32 v27, v2
	v_mov_b32_e32 v28, v2
	v_mov_b32_e32 v29, v2
	v_mov_b32_e32 v30, v2
	v_mov_b32_e32 v31, v2
	v_mov_b32_e32 v32, v2
	v_mov_b32_e32 v33, v2
	v_mov_b32_e32 v42, v2
	v_mov_b32_e32 v43, v2
	v_mov_b32_e32 v44, v2
	v_mov_b32_e32 v45, v2
	v_mov_b32_e32 v46, v2
	v_mov_b32_e32 v47, v2
	v_mov_b32_e32 v48, v2
	v_mov_b32_e32 v49, v2
	v_mov_b32_e32 v18, v2
	v_mov_b32_e32 v19, v2
	v_mov_b32_e32 v20, v2
	v_mov_b32_e32 v21, v2
	v_mov_b32_e32 v22, v2
	v_mov_b32_e32 v23, v2
	v_mov_b32_e32 v24, v2
	v_mov_b32_e32 v25, v2
	v_mov_b32_e32 v34, v2
	v_mov_b32_e32 v35, v2
	v_mov_b32_e32 v36, v2
	v_mov_b32_e32 v37, v2
	v_mov_b32_e32 v38, v2
	v_mov_b32_e32 v39, v2
	v_mov_b32_e32 v40, v2
	v_mov_b32_e32 v41, v2
	v_mov_b32_e32 v50, v2
	v_mov_b32_e32 v51, v2
	v_mov_b32_e32 v52, v2
	v_mov_b32_e32 v53, v2
	v_mov_b32_e32 v54, v2
	v_mov_b32_e32 v55, v2
	v_mov_b32_e32 v56, v2
	v_mov_b32_e32 v57, v2
	v_mov_b32_e32 v58, v2
	v_mov_b32_e32 v59, v2
	v_mov_b32_e32 v60, v2
	v_mov_b32_e32 v61, v2
	v_mov_b32_e32 v62, v2
	v_mov_b32_e32 v63, v2
	v_mov_b32_e32 v64, v2
	v_mov_b32_e32 v65, v2
	v_mov_b32_e32 v66, v2
	v_mov_b32_e32 v67, v2
	v_mov_b32_e32 v68, v2
	v_mov_b32_e32 v69, v2
	v_mov_b32_e32 v70, v2
	v_mov_b32_e32 v71, v2
	v_mov_b32_e32 v72, v2
	v_mov_b32_e32 v73, v2
	v_mov_b32_e32 v74, v2
	v_mov_b32_e32 v75, v2
	v_mov_b32_e32 v76, v2
	v_mov_b32_e32 v77, v2
	v_mov_b32_e32 v78, v2
	v_mov_b32_e32 v79, v2
	v_mov_b32_e32 v80, v2
	v_mov_b32_e32 v81, v2
	v_mov_b32_e32 v90, v2
	v_mov_b32_e32 v91, v2
	v_mov_b32_e32 v92, v2
	v_mov_b32_e32 v93, v2
	v_mov_b32_e32 v94, v2
	v_mov_b32_e32 v95, v2
	v_mov_b32_e32 v96, v2
	v_mov_b32_e32 v97, v2
	v_mov_b32_e32 v106, v2
	v_mov_b32_e32 v107, v2
	v_mov_b32_e32 v108, v2
	v_mov_b32_e32 v109, v2
	v_mov_b32_e32 v110, v2
	v_mov_b32_e32 v111, v2
	v_mov_b32_e32 v112, v2
	v_mov_b32_e32 v113, v2
	v_mov_b32_e32 v82, v2
	v_mov_b32_e32 v83, v2
	v_mov_b32_e32 v84, v2
	v_mov_b32_e32 v85, v2
	v_mov_b32_e32 v86, v2
	v_mov_b32_e32 v87, v2
	v_mov_b32_e32 v88, v2
	v_mov_b32_e32 v89, v2
	v_mov_b32_e32 v98, v2
	v_mov_b32_e32 v99, v2
	v_mov_b32_e32 v100, v2
	v_mov_b32_e32 v101, v2
	v_mov_b32_e32 v102, v2
	v_mov_b32_e32 v103, v2
	v_mov_b32_e32 v104, v2
	v_mov_b32_e32 v105, v2
	v_mov_b32_e32 v114, v2
	v_mov_b32_e32 v115, v2
	v_mov_b32_e32 v116, v2
	v_mov_b32_e32 v117, v2
	v_mov_b32_e32 v118, v2
	v_mov_b32_e32 v119, v2
	v_mov_b32_e32 v120, v2
	v_mov_b32_e32 v121, v2
	v_mov_b32_e32 v122, v2
	v_mov_b32_e32 v123, v2
	v_mov_b32_e32 v124, v2
	v_mov_b32_e32 v125, v2
	v_mov_b32_e32 v126, v2
	v_mov_b32_e32 v127, v2
	v_mov_b32_e32 v128, v2
	v_mov_b32_e32 v129, v2
	s_cmp_lg_u32 s100, 0
	s_cbranch_scc1 .Lup_peel
.LBB0_177:
	s_add_u32 s22, s18, 0xfffc0080
	s_addc_u32 s23, s19, -1
	s_add_i32 s56, 0, 0x10000
	v_add_u32_e32 v148, s56, v141
	ds_read_b128 v[144:147], v148
	ds_read_b128 v[160:163], v148 offset:1024
	ds_read_b128 v[164:167], v148 offset:2048
	ds_read_b128 v[168:171], v148 offset:3072
	s_cmp_eq_u32 s55, 12
	s_cselect_b32 s25, s11, s23
	s_cselect_b32 s24, s51, s22
	s_cselect_b32 s23, s9, s54
	s_cselect_b32 s22, s52, s53
	v_lshl_add_u64 v[148:149], s[18:19], 0, v[138:139]
	s_add_i32 m0, s3, 0xc000
	ds_read_b128 v[172:175], v143
	ds_read_b128 v[176:179], v143 offset:1024
	ds_read_b128 v[180:183], v143 offset:2048
	ds_read_b128 v[184:187], v143 offset:3072
	ds_read_b128 v[188:191], v143 offset:4096
	ds_read_b128 v[192:195], v143 offset:5120
	ds_read_b128 v[196:199], v143 offset:6144
	ds_read_b128 v[200:203], v143 offset:7168
	global_load_lds_dwordx4 v[148:149], off
	v_lshl_add_u64 v[148:149], s[18:19], 0, v[136:137]
	s_add_i32 m0, s3, 0xe000
	s_nop 0
	global_load_lds_dwordx4 v[148:149], off
	s_waitcnt lgkmcnt(8)
	s_barrier
	s_waitcnt lgkmcnt(0)
	s_setprio 1
	s_waitcnt lgkmcnt(0)
	v_mfma_f32_16x16x32_bf16 v[126:129], v[144:147], v[172:175], v[126:129]
	v_mfma_f32_16x16x32_bf16 v[122:125], v[164:167], v[172:175], v[122:125]
	v_mfma_f32_16x16x32_bf16 v[118:121], v[144:147], v[180:183], v[118:121]
	v_mfma_f32_16x16x32_bf16 v[114:117], v[164:167], v[180:183], v[114:117]
	v_mfma_f32_16x16x32_bf16 v[102:105], v[144:147], v[188:191], v[102:105]
	v_mfma_f32_16x16x32_bf16 v[98:101], v[164:167], v[188:191], v[98:101]
	v_mfma_f32_16x16x32_bf16 v[86:89], v[144:147], v[196:199], v[86:89]
	v_mfma_f32_16x16x32_bf16 v[82:85], v[164:167], v[196:199], v[82:85]
	v_mfma_f32_16x16x32_bf16 v[126:129], v[160:163], v[176:179], v[126:129]
	v_mfma_f32_16x16x32_bf16 v[122:125], v[168:171], v[176:179], v[122:125]
	v_mfma_f32_16x16x32_bf16 v[118:121], v[160:163], v[184:187], v[118:121]
	v_mfma_f32_16x16x32_bf16 v[114:117], v[168:171], v[184:187], v[114:117]
	v_mfma_f32_16x16x32_bf16 v[102:105], v[160:163], v[192:195], v[102:105]
	v_mfma_f32_16x16x32_bf16 v[98:101], v[168:171], v[192:195], v[98:101]
	v_mfma_f32_16x16x32_bf16 v[86:89], v[160:163], v[200:203], v[86:89]
	v_mfma_f32_16x16x32_bf16 v[82:85], v[168:171], v[200:203], v[82:85]
	s_setprio 0
	s_barrier
	s_add_i32 s58, 0, 0x14000
	v_add_u32_e32 v148, s58, v141
	s_add_i32 s56, s56, s29
	ds_read_b128 v[234:237], v148
	ds_read_b128 v[238:241], v148 offset:1024
	ds_read_b128 v[242:245], v148 offset:2048
	ds_read_b128 v[246:249], v148 offset:3072
	v_lshl_add_u64 v[148:149], s[22:23], 0, v[0:1]
	s_mov_b32 m0, s56
	v_lshl_add_u64 v[204:205], s[22:23], 0, v[130:131]
	global_load_lds_dwordx4 v[148:149], off
	s_add_i32 m0, s56, 0x2000
	s_nop 0
	global_load_lds_dwordx4 v[204:205], off
	s_barrier
	s_waitcnt lgkmcnt(0)
	s_setprio 1
	s_waitcnt lgkmcnt(0)
	v_mfma_f32_16x16x32_bf16 v[110:113], v[234:237], v[172:175], v[110:113]
	v_mfma_f32_16x16x32_bf16 v[106:109], v[242:245], v[172:175], v[106:109]
	v_mfma_f32_16x16x32_bf16 v[94:97], v[234:237], v[180:183], v[94:97]
	v_mfma_f32_16x16x32_bf16 v[90:93], v[242:245], v[180:183], v[90:93]
	v_mfma_f32_16x16x32_bf16 v[78:81], v[234:237], v[188:191], v[78:81]
	v_mfma_f32_16x16x32_bf16 v[74:77], v[242:245], v[188:191], v[74:77]
	v_mfma_f32_16x16x32_bf16 v[70:73], v[234:237], v[196:199], v[70:73]
	v_mfma_f32_16x16x32_bf16 v[66:69], v[242:245], v[196:199], v[66:69]
	v_mfma_f32_16x16x32_bf16 v[110:113], v[238:241], v[176:179], v[110:113]
	v_mfma_f32_16x16x32_bf16 v[106:109], v[246:249], v[176:179], v[106:109]
	v_mfma_f32_16x16x32_bf16 v[94:97], v[238:241], v[184:187], v[94:97]
	v_mfma_f32_16x16x32_bf16 v[90:93], v[246:249], v[184:187], v[90:93]
	v_mfma_f32_16x16x32_bf16 v[78:81], v[238:241], v[192:195], v[78:81]
	v_mfma_f32_16x16x32_bf16 v[74:77], v[246:249], v[192:195], v[74:77]
	v_mfma_f32_16x16x32_bf16 v[70:73], v[238:241], v[200:203], v[70:73]
	v_mfma_f32_16x16x32_bf16 v[66:69], v[246:249], v[200:203], v[66:69]
	s_setprio 0
	s_mov_b32 m0, s3
	v_lshl_add_u64 v[250:251], s[24:25], 0, v[134:135]
	s_barrier
	ds_read_b128 v[172:175], v143 offset:16384
	ds_read_b128 v[176:179], v143 offset:17408
	ds_read_b128 v[180:183], v143 offset:18432
	ds_read_b128 v[184:187], v143 offset:19456
	ds_read_b128 v[188:191], v143 offset:20480
	ds_read_b128 v[192:195], v143 offset:21504
	ds_read_b128 v[196:199], v143 offset:22528
	ds_read_b128 v[200:203], v143 offset:23552
	global_load_lds_dwordx4 v[250:251], off
	v_lshl_add_u64 v[252:253], s[24:25], 0, v[132:133]
	s_mov_b32 m0, s35
	s_nop 0
	global_load_lds_dwordx4 v[252:253], off
	s_barrier
	s_waitcnt lgkmcnt(0)
	s_setprio 1
	s_waitcnt lgkmcnt(0)
	v_mfma_f32_16x16x32_bf16 v[62:65], v[144:147], v[172:175], v[62:65]
	v_mfma_f32_16x16x32_bf16 v[58:61], v[164:167], v[172:175], v[58:61]
	v_mfma_f32_16x16x32_bf16 v[54:57], v[144:147], v[180:183], v[54:57]
	v_mfma_f32_16x16x32_bf16 v[50:53], v[164:167], v[180:183], v[50:53]
	v_mfma_f32_16x16x32_bf16 v[38:41], v[144:147], v[188:191], v[38:41]
	v_mfma_f32_16x16x32_bf16 v[34:37], v[164:167], v[188:191], v[34:37]
	v_mfma_f32_16x16x32_bf16 v[22:25], v[144:147], v[196:199], v[22:25]
	v_mfma_f32_16x16x32_bf16 v[18:21], v[164:167], v[196:199], v[18:21]
	v_mfma_f32_16x16x32_bf16 v[62:65], v[160:163], v[176:179], v[62:65]
	v_mfma_f32_16x16x32_bf16 v[58:61], v[168:171], v[176:179], v[58:61]
	v_mfma_f32_16x16x32_bf16 v[54:57], v[160:163], v[184:187], v[54:57]
	v_mfma_f32_16x16x32_bf16 v[50:53], v[168:171], v[184:187], v[50:53]
	v_mfma_f32_16x16x32_bf16 v[38:41], v[160:163], v[192:195], v[38:41]
	v_mfma_f32_16x16x32_bf16 v[34:37], v[168:171], v[192:195], v[34:37]
	v_mfma_f32_16x16x32_bf16 v[22:25], v[160:163], v[200:203], v[22:25]
	v_mfma_f32_16x16x32_bf16 v[18:21], v[168:171], v[200:203], v[18:21]
	s_setprio 0
	s_barrier
	s_add_u32 s56, s22, 0x40000
	s_addc_u32 s57, s23, 0
	s_add_i32 s58, s58, s29
	v_lshl_add_u64 v[144:145], s[56:57], 0, v[0:1]
	s_mov_b32 m0, s58
	s_nop 0
	global_load_lds_dwordx4 v[144:145], off
	v_lshl_add_u64 v[144:145], s[56:57], 0, v[130:131]
	s_add_i32 m0, s58, 0x2000
	s_nop 0
	global_load_lds_dwordx4 v[144:145], off
	s_waitcnt vmcnt(6)
	s_barrier
	s_setprio 1
	v_mfma_f32_16x16x32_bf16 v[46:49], v[234:237], v[172:175], v[46:49]
	v_mfma_f32_16x16x32_bf16 v[42:45], v[242:245], v[172:175], v[42:45]
	v_mfma_f32_16x16x32_bf16 v[30:33], v[234:237], v[180:183], v[30:33]
	v_mfma_f32_16x16x32_bf16 v[26:29], v[242:245], v[180:183], v[26:29]
	v_mfma_f32_16x16x32_bf16 v[14:17], v[234:237], v[188:191], v[14:17]
	v_mfma_f32_16x16x32_bf16 v[10:13], v[242:245], v[188:191], v[10:13]
	v_mfma_f32_16x16x32_bf16 v[6:9], v[234:237], v[196:199], v[6:9]
	v_mfma_f32_16x16x32_bf16 v[2:5], v[242:245], v[196:199], v[2:5]
	v_mfma_f32_16x16x32_bf16 v[46:49], v[238:241], v[176:179], v[46:49]
	v_mfma_f32_16x16x32_bf16 v[42:45], v[246:249], v[176:179], v[42:45]
	v_mfma_f32_16x16x32_bf16 v[30:33], v[238:241], v[184:187], v[30:33]
	v_mfma_f32_16x16x32_bf16 v[26:29], v[246:249], v[184:187], v[26:29]
	v_mfma_f32_16x16x32_bf16 v[14:17], v[238:241], v[192:195], v[14:17]
	v_mfma_f32_16x16x32_bf16 v[10:13], v[246:249], v[192:195], v[10:13]
	v_mfma_f32_16x16x32_bf16 v[6:9], v[238:241], v[200:203], v[6:9]
	v_mfma_f32_16x16x32_bf16 v[2:5], v[246:249], v[200:203], v[2:5]
	s_setprio 0
	s_add_i32 s56, 0, 0x18000
	v_add_u32_e32 v159, s56, v141
	s_barrier
	ds_read_b128 v[144:147], v159
	ds_read_b128 v[160:163], v159 offset:1024
	ds_read_b128 v[164:167], v159 offset:2048
	ds_read_b128 v[168:171], v159 offset:3072
	s_add_u32 s24, s24, 0x40000
	s_addc_u32 s25, s25, 0
	s_mov_b32 m0, s38
	v_lshl_add_u64 v[234:235], s[24:25], 0, v[134:135]
	ds_read_b128 v[172:175], v143 offset:32768
	ds_read_b128 v[176:179], v143 offset:33792
	ds_read_b128 v[180:183], v143 offset:34816
	ds_read_b128 v[184:187], v143 offset:35840
	ds_read_b128 v[188:191], v143 offset:36864
	ds_read_b128 v[192:195], v143 offset:37888
	ds_read_b128 v[196:199], v143 offset:38912
	ds_read_b128 v[200:203], v143 offset:39936
	global_load_lds_dwordx4 v[234:235], off
	v_lshl_add_u64 v[234:235], s[24:25], 0, v[132:133]
	s_mov_b32 m0, s39
	s_nop 0
	global_load_lds_dwordx4 v[234:235], off
	s_waitcnt lgkmcnt(8)
	s_barrier
	s_waitcnt lgkmcnt(0)
	s_setprio 1
	s_waitcnt lgkmcnt(0)
	v_mfma_f32_16x16x32_bf16 v[126:129], v[144:147], v[172:175], v[126:129]
	v_mfma_f32_16x16x32_bf16 v[122:125], v[164:167], v[172:175], v[122:125]
	v_mfma_f32_16x16x32_bf16 v[118:121], v[144:147], v[180:183], v[118:121]
	v_mfma_f32_16x16x32_bf16 v[114:117], v[164:167], v[180:183], v[114:117]
	v_mfma_f32_16x16x32_bf16 v[102:105], v[144:147], v[188:191], v[102:105]
	v_mfma_f32_16x16x32_bf16 v[98:101], v[164:167], v[188:191], v[98:101]
	v_mfma_f32_16x16x32_bf16 v[86:89], v[144:147], v[196:199], v[86:89]
	v_mfma_f32_16x16x32_bf16 v[82:85], v[164:167], v[196:199], v[82:85]
	v_mfma_f32_16x16x32_bf16 v[126:129], v[160:163], v[176:179], v[126:129]
	v_mfma_f32_16x16x32_bf16 v[122:125], v[168:171], v[176:179], v[122:125]
	v_mfma_f32_16x16x32_bf16 v[118:121], v[160:163], v[184:187], v[118:121]
	v_mfma_f32_16x16x32_bf16 v[114:117], v[168:171], v[184:187], v[114:117]
	v_mfma_f32_16x16x32_bf16 v[102:105], v[160:163], v[192:195], v[102:105]
	v_mfma_f32_16x16x32_bf16 v[98:101], v[168:171], v[192:195], v[98:101]
	v_mfma_f32_16x16x32_bf16 v[86:89], v[160:163], v[200:203], v[86:89]
	v_mfma_f32_16x16x32_bf16 v[82:85], v[168:171], v[200:203], v[82:85]
	s_setprio 0
	s_barrier
	s_add_i32 s24, 0, 0x1c000
	s_add_i32 s25, s56, s29
	v_add_u32_e32 v159, s24, v141
	v_lshl_add_u64 v[148:149], v[148:149], 0, s[20:21]
	s_mov_b32 m0, s25
	ds_read_b128 v[234:237], v159
	ds_read_b128 v[238:241], v159 offset:1024
	ds_read_b128 v[242:245], v159 offset:2048
	ds_read_b128 v[246:249], v159 offset:3072
	global_load_lds_dwordx4 v[148:149], off
	v_lshl_add_u64 v[148:149], v[204:205], 0, s[20:21]
	s_add_i32 m0, s25, 0x2000
	s_nop 0
	global_load_lds_dwordx4 v[148:149], off
	s_barrier
	s_waitcnt lgkmcnt(0)
	s_setprio 1
	s_waitcnt lgkmcnt(0)
	v_mfma_f32_16x16x32_bf16 v[110:113], v[234:237], v[172:175], v[110:113]
	v_mfma_f32_16x16x32_bf16 v[106:109], v[242:245], v[172:175], v[106:109]
	v_mfma_f32_16x16x32_bf16 v[94:97], v[234:237], v[180:183], v[94:97]
	v_mfma_f32_16x16x32_bf16 v[90:93], v[242:245], v[180:183], v[90:93]
	v_mfma_f32_16x16x32_bf16 v[78:81], v[234:237], v[188:191], v[78:81]
	v_mfma_f32_16x16x32_bf16 v[74:77], v[242:245], v[188:191], v[74:77]
	v_mfma_f32_16x16x32_bf16 v[70:73], v[234:237], v[196:199], v[70:73]
	v_mfma_f32_16x16x32_bf16 v[66:69], v[242:245], v[196:199], v[66:69]
	v_mfma_f32_16x16x32_bf16 v[110:113], v[238:241], v[176:179], v[110:113]
	v_mfma_f32_16x16x32_bf16 v[106:109], v[246:249], v[176:179], v[106:109]
	v_mfma_f32_16x16x32_bf16 v[94:97], v[238:241], v[184:187], v[94:97]
	v_mfma_f32_16x16x32_bf16 v[90:93], v[246:249], v[184:187], v[90:93]
	v_mfma_f32_16x16x32_bf16 v[78:81], v[238:241], v[192:195], v[78:81]
	v_mfma_f32_16x16x32_bf16 v[74:77], v[246:249], v[192:195], v[74:77]
	v_mfma_f32_16x16x32_bf16 v[70:73], v[238:241], v[200:203], v[70:73]
	v_mfma_f32_16x16x32_bf16 v[66:69], v[246:249], v[200:203], v[66:69]
	s_setprio 0
	s_mov_b32 m0, s42
	v_lshl_add_u64 v[148:149], v[250:251], 0, s[20:21]
	s_barrier
	ds_read_b128 v[172:175], v143 offset:49152
	ds_read_b128 v[176:179], v143 offset:50176
	ds_read_b128 v[180:183], v143 offset:51200
	ds_read_b128 v[184:187], v143 offset:52224
	ds_read_b128 v[188:191], v143 offset:53248
	ds_read_b128 v[192:195], v143 offset:54272
	ds_read_b128 v[196:199], v143 offset:55296
	ds_read_b128 v[200:203], v143 offset:56320
	global_load_lds_dwordx4 v[148:149], off
	v_lshl_add_u64 v[148:149], v[252:253], 0, s[20:21]
	s_mov_b32 m0, s43
	s_nop 0
	global_load_lds_dwordx4 v[148:149], off
	s_barrier
	s_waitcnt lgkmcnt(0)
	s_setprio 1
	s_waitcnt lgkmcnt(0)
	v_mfma_f32_16x16x32_bf16 v[62:65], v[144:147], v[172:175], v[62:65]
	v_mfma_f32_16x16x32_bf16 v[58:61], v[164:167], v[172:175], v[58:61]
	v_mfma_f32_16x16x32_bf16 v[54:57], v[144:147], v[180:183], v[54:57]
	v_mfma_f32_16x16x32_bf16 v[50:53], v[164:167], v[180:183], v[50:53]
	v_mfma_f32_16x16x32_bf16 v[38:41], v[144:147], v[188:191], v[38:41]
	v_mfma_f32_16x16x32_bf16 v[34:37], v[164:167], v[188:191], v[34:37]
	v_mfma_f32_16x16x32_bf16 v[22:25], v[144:147], v[196:199], v[22:25]
	v_mfma_f32_16x16x32_bf16 v[18:21], v[164:167], v[196:199], v[18:21]
	v_mfma_f32_16x16x32_bf16 v[62:65], v[160:163], v[176:179], v[62:65]
	v_mfma_f32_16x16x32_bf16 v[58:61], v[168:171], v[176:179], v[58:61]
	v_mfma_f32_16x16x32_bf16 v[54:57], v[160:163], v[184:187], v[54:57]
	v_mfma_f32_16x16x32_bf16 v[50:53], v[168:171], v[184:187], v[50:53]
	v_mfma_f32_16x16x32_bf16 v[38:41], v[160:163], v[192:195], v[38:41]
	v_mfma_f32_16x16x32_bf16 v[34:37], v[168:171], v[192:195], v[34:37]
	v_mfma_f32_16x16x32_bf16 v[22:25], v[160:163], v[200:203], v[22:25]
	v_mfma_f32_16x16x32_bf16 v[18:21], v[168:171], v[200:203], v[18:21]
	s_setprio 0
	s_barrier
	s_add_u32 s22, s22, 0x40080
	s_addc_u32 s23, s23, 0
	s_add_i32 s24, s24, s29
	v_lshl_add_u64 v[144:145], s[22:23], 0, v[0:1]
	s_mov_b32 m0, s24
	s_nop 0
	global_load_lds_dwordx4 v[144:145], off
	v_lshl_add_u64 v[144:145], s[22:23], 0, v[130:131]
	s_add_i32 m0, s24, 0x2000
	s_nop 0
	global_load_lds_dwordx4 v[144:145], off
	s_waitcnt vmcnt(6)
	s_barrier
	s_setprio 1
	v_mfma_f32_16x16x32_bf16 v[46:49], v[234:237], v[172:175], v[46:49]
	v_mfma_f32_16x16x32_bf16 v[42:45], v[242:245], v[172:175], v[42:45]
	v_mfma_f32_16x16x32_bf16 v[30:33], v[234:237], v[180:183], v[30:33]
	v_mfma_f32_16x16x32_bf16 v[26:29], v[242:245], v[180:183], v[26:29]
	v_mfma_f32_16x16x32_bf16 v[14:17], v[234:237], v[188:191], v[14:17]
	v_mfma_f32_16x16x32_bf16 v[10:13], v[242:245], v[188:191], v[10:13]
	v_mfma_f32_16x16x32_bf16 v[6:9], v[234:237], v[196:199], v[6:9]
	v_mfma_f32_16x16x32_bf16 v[2:5], v[242:245], v[196:199], v[2:5]
	v_mfma_f32_16x16x32_bf16 v[46:49], v[238:241], v[176:179], v[46:49]
	v_mfma_f32_16x16x32_bf16 v[42:45], v[246:249], v[176:179], v[42:45]
	v_mfma_f32_16x16x32_bf16 v[30:33], v[238:241], v[184:187], v[30:33]
	v_mfma_f32_16x16x32_bf16 v[26:29], v[246:249], v[184:187], v[26:29]
	v_mfma_f32_16x16x32_bf16 v[14:17], v[238:241], v[192:195], v[14:17]
	v_mfma_f32_16x16x32_bf16 v[10:13], v[246:249], v[192:195], v[10:13]
	v_mfma_f32_16x16x32_bf16 v[6:9], v[238:241], v[200:203], v[6:9]
	v_mfma_f32_16x16x32_bf16 v[2:5], v[246:249], v[200:203], v[2:5]
	s_setprio 0
	s_add_i32 s55, s55, 2
	s_add_u32 s53, s53, 0x100
	s_addc_u32 s54, s54, 0
	s_add_u32 s18, s18, 0x100
	s_addc_u32 s19, s19, 0
	s_cmp_gt_u32 s55, 13
	s_barrier
	s_cbranch_scc0 .LBB0_177
	s_branch .Lup_epi
.Lup_peel:
	s_add_u32 s22, s18, 0xfffc0080
	s_addc_u32 s23, s19, -1
	s_add_i32 s56, 0, 0x10000
	v_add_u32_e32 v148, s56, v141
	ds_read_b128 v[144:147], v148
	ds_read_b128 v[160:163], v148 offset:1024
	ds_read_b128 v[164:167], v148 offset:2048
	ds_read_b128 v[168:171], v148 offset:3072
	s_cmp_eq_u32 s55, 12
	s_cselect_b32 s25, s11, s23
	s_cselect_b32 s24, s51, s22
	s_cselect_b32 s23, s9, s54
	s_cselect_b32 s22, s52, s53
	v_lshl_add_u64 v[148:149], s[18:19], 0, v[138:139]
	s_add_i32 m0, s3, 0xc000
	ds_read_b128 v[172:175], v143
	ds_read_b128 v[176:179], v143 offset:1024
	ds_read_b128 v[180:183], v143 offset:2048
	ds_read_b128 v[184:187], v143 offset:3072
	ds_read_b128 v[188:191], v143 offset:4096
	ds_read_b128 v[192:195], v143 offset:5120
	ds_read_b128 v[196:199], v143 offset:6144
	ds_read_b128 v[200:203], v143 offset:7168
	v_lshl_add_u64 v[148:149], s[18:19], 0, v[136:137]
	s_add_i32 m0, s3, 0xe000
	s_nop 0
	s_waitcnt lgkmcnt(8)
	s_barrier
	s_waitcnt lgkmcnt(0)
	s_setprio 1
	s_waitcnt lgkmcnt(0)
	v_mfma_f32_16x16x32_bf16 v[126:129], v[144:147], v[172:175], v[126:129]
	v_mfma_f32_16x16x32_bf16 v[122:125], v[164:167], v[172:175], v[122:125]
	v_mfma_f32_16x16x32_bf16 v[118:121], v[144:147], v[180:183], v[118:121]
	v_mfma_f32_16x16x32_bf16 v[114:117], v[164:167], v[180:183], v[114:117]
	v_mfma_f32_16x16x32_bf16 v[102:105], v[144:147], v[188:191], v[102:105]
	v_mfma_f32_16x16x32_bf16 v[98:101], v[164:167], v[188:191], v[98:101]
	v_mfma_f32_16x16x32_bf16 v[86:89], v[144:147], v[196:199], v[86:89]
	v_mfma_f32_16x16x32_bf16 v[82:85], v[164:167], v[196:199], v[82:85]
	v_mfma_f32_16x16x32_bf16 v[126:129], v[160:163], v[176:179], v[126:129]
	v_mfma_f32_16x16x32_bf16 v[122:125], v[168:171], v[176:179], v[122:125]
	v_mfma_f32_16x16x32_bf16 v[118:121], v[160:163], v[184:187], v[118:121]
	v_mfma_f32_16x16x32_bf16 v[114:117], v[168:171], v[184:187], v[114:117]
	v_mfma_f32_16x16x32_bf16 v[102:105], v[160:163], v[192:195], v[102:105]
	v_mfma_f32_16x16x32_bf16 v[98:101], v[168:171], v[192:195], v[98:101]
	v_mfma_f32_16x16x32_bf16 v[86:89], v[160:163], v[200:203], v[86:89]
	v_mfma_f32_16x16x32_bf16 v[82:85], v[168:171], v[200:203], v[82:85]
	s_setprio 0
	s_barrier
	s_add_i32 s58, 0, 0x14000
	v_add_u32_e32 v148, s58, v141
	s_add_i32 s56, s56, s29
	ds_read_b128 v[234:237], v148
	ds_read_b128 v[238:241], v148 offset:1024
	ds_read_b128 v[242:245], v148 offset:2048
	ds_read_b128 v[246:249], v148 offset:3072
	v_lshl_add_u64 v[148:149], s[22:23], 0, v[0:1]
	s_mov_b32 m0, s56
	v_lshl_add_u64 v[204:205], s[22:23], 0, v[130:131]
	global_load_lds_dwordx4 v[148:149], off
	s_add_i32 m0, s56, 0x2000
	s_nop 0
	global_load_lds_dwordx4 v[204:205], off
	s_barrier
	s_waitcnt lgkmcnt(0)
	s_setprio 1
	s_waitcnt lgkmcnt(0)
	v_mfma_f32_16x16x32_bf16 v[110:113], v[234:237], v[172:175], v[110:113]
	v_mfma_f32_16x16x32_bf16 v[106:109], v[242:245], v[172:175], v[106:109]
	v_mfma_f32_16x16x32_bf16 v[94:97], v[234:237], v[180:183], v[94:97]
	v_mfma_f32_16x16x32_bf16 v[90:93], v[242:245], v[180:183], v[90:93]
	v_mfma_f32_16x16x32_bf16 v[78:81], v[234:237], v[188:191], v[78:81]
	v_mfma_f32_16x16x32_bf16 v[74:77], v[242:245], v[188:191], v[74:77]
	v_mfma_f32_16x16x32_bf16 v[70:73], v[234:237], v[196:199], v[70:73]
	v_mfma_f32_16x16x32_bf16 v[66:69], v[242:245], v[196:199], v[66:69]
	v_mfma_f32_16x16x32_bf16 v[110:113], v[238:241], v[176:179], v[110:113]
	v_mfma_f32_16x16x32_bf16 v[106:109], v[246:249], v[176:179], v[106:109]
	v_mfma_f32_16x16x32_bf16 v[94:97], v[238:241], v[184:187], v[94:97]
	v_mfma_f32_16x16x32_bf16 v[90:93], v[246:249], v[184:187], v[90:93]
	v_mfma_f32_16x16x32_bf16 v[78:81], v[238:241], v[192:195], v[78:81]
	v_mfma_f32_16x16x32_bf16 v[74:77], v[246:249], v[192:195], v[74:77]
	v_mfma_f32_16x16x32_bf16 v[70:73], v[238:241], v[200:203], v[70:73]
	v_mfma_f32_16x16x32_bf16 v[66:69], v[246:249], v[200:203], v[66:69]
	s_setprio 0
	s_mov_b32 m0, s3
	v_lshl_add_u64 v[250:251], s[24:25], 0, v[134:135]
	s_barrier
	ds_read_b128 v[172:175], v143 offset:16384
	ds_read_b128 v[176:179], v143 offset:17408
	ds_read_b128 v[180:183], v143 offset:18432
	ds_read_b128 v[184:187], v143 offset:19456
	ds_read_b128 v[188:191], v143 offset:20480
	ds_read_b128 v[192:195], v143 offset:21504
	ds_read_b128 v[196:199], v143 offset:22528
	ds_read_b128 v[200:203], v143 offset:23552
	global_load_lds_dwordx4 v[250:251], off
	v_lshl_add_u64 v[252:253], s[24:25], 0, v[132:133]
	s_mov_b32 m0, s35
	s_nop 0
	global_load_lds_dwordx4 v[252:253], off
	s_barrier
	s_waitcnt lgkmcnt(0)
	s_setprio 1
	s_waitcnt lgkmcnt(0)
	v_mfma_f32_16x16x32_bf16 v[62:65], v[144:147], v[172:175], v[62:65]
	v_mfma_f32_16x16x32_bf16 v[58:61], v[164:167], v[172:175], v[58:61]
	v_mfma_f32_16x16x32_bf16 v[54:57], v[144:147], v[180:183], v[54:57]
	v_mfma_f32_16x16x32_bf16 v[50:53], v[164:167], v[180:183], v[50:53]
	v_mfma_f32_16x16x32_bf16 v[38:41], v[144:147], v[188:191], v[38:41]
	v_mfma_f32_16x16x32_bf16 v[34:37], v[164:167], v[188:191], v[34:37]
	v_mfma_f32_16x16x32_bf16 v[22:25], v[144:147], v[196:199], v[22:25]
	v_mfma_f32_16x16x32_bf16 v[18:21], v[164:167], v[196:199], v[18:21]
	v_mfma_f32_16x16x32_bf16 v[62:65], v[160:163], v[176:179], v[62:65]
	v_mfma_f32_16x16x32_bf16 v[58:61], v[168:171], v[176:179], v[58:61]
	v_mfma_f32_16x16x32_bf16 v[54:57], v[160:163], v[184:187], v[54:57]
	v_mfma_f32_16x16x32_bf16 v[50:53], v[168:171], v[184:187], v[50:53]
	v_mfma_f32_16x16x32_bf16 v[38:41], v[160:163], v[192:195], v[38:41]
	v_mfma_f32_16x16x32_bf16 v[34:37], v[168:171], v[192:195], v[34:37]
	v_mfma_f32_16x16x32_bf16 v[22:25], v[160:163], v[200:203], v[22:25]
	v_mfma_f32_16x16x32_bf16 v[18:21], v[168:171], v[200:203], v[18:21]
	s_setprio 0
	s_barrier
	s_add_u32 s56, s22, 0x40000
	s_addc_u32 s57, s23, 0
	s_add_i32 s58, s58, s29
	v_lshl_add_u64 v[144:145], s[56:57], 0, v[0:1]
	s_mov_b32 m0, s58
	s_nop 0
	global_load_lds_dwordx4 v[144:145], off
	v_lshl_add_u64 v[144:145], s[56:57], 0, v[130:131]
	s_add_i32 m0, s58, 0x2000
	s_nop 0
	global_load_lds_dwordx4 v[144:145], off
	s_waitcnt vmcnt(22)
	s_barrier
	s_setprio 1
	v_mfma_f32_16x16x32_bf16 v[46:49], v[234:237], v[172:175], v[46:49]
	v_mfma_f32_16x16x32_bf16 v[42:45], v[242:245], v[172:175], v[42:45]
	v_mfma_f32_16x16x32_bf16 v[30:33], v[234:237], v[180:183], v[30:33]
	v_mfma_f32_16x16x32_bf16 v[26:29], v[242:245], v[180:183], v[26:29]
	v_mfma_f32_16x16x32_bf16 v[14:17], v[234:237], v[188:191], v[14:17]
	v_mfma_f32_16x16x32_bf16 v[10:13], v[242:245], v[188:191], v[10:13]
	v_mfma_f32_16x16x32_bf16 v[6:9], v[234:237], v[196:199], v[6:9]
	v_mfma_f32_16x16x32_bf16 v[2:5], v[242:245], v[196:199], v[2:5]
	v_mfma_f32_16x16x32_bf16 v[46:49], v[238:241], v[176:179], v[46:49]
	v_mfma_f32_16x16x32_bf16 v[42:45], v[246:249], v[176:179], v[42:45]
	v_mfma_f32_16x16x32_bf16 v[30:33], v[238:241], v[184:187], v[30:33]
	v_mfma_f32_16x16x32_bf16 v[26:29], v[246:249], v[184:187], v[26:29]
	v_mfma_f32_16x16x32_bf16 v[14:17], v[238:241], v[192:195], v[14:17]
	v_mfma_f32_16x16x32_bf16 v[10:13], v[246:249], v[192:195], v[10:13]
	v_mfma_f32_16x16x32_bf16 v[6:9], v[238:241], v[200:203], v[6:9]
	v_mfma_f32_16x16x32_bf16 v[2:5], v[246:249], v[200:203], v[2:5]
	s_setprio 0
	s_add_i32 s56, 0, 0x18000
	v_add_u32_e32 v159, s56, v141
	s_barrier
	ds_read_b128 v[144:147], v159
	ds_read_b128 v[160:163], v159 offset:1024
	ds_read_b128 v[164:167], v159 offset:2048
	ds_read_b128 v[168:171], v159 offset:3072
	s_add_u32 s24, s24, 0x40000
	s_addc_u32 s25, s25, 0
	s_mov_b32 m0, s38
	v_lshl_add_u64 v[234:235], s[24:25], 0, v[134:135]
	ds_read_b128 v[172:175], v143 offset:32768
	ds_read_b128 v[176:179], v143 offset:33792
	ds_read_b128 v[180:183], v143 offset:34816
	ds_read_b128 v[184:187], v143 offset:35840
	ds_read_b128 v[188:191], v143 offset:36864
	ds_read_b128 v[192:195], v143 offset:37888
	ds_read_b128 v[196:199], v143 offset:38912
	ds_read_b128 v[200:203], v143 offset:39936
	global_load_lds_dwordx4 v[234:235], off
	v_lshl_add_u64 v[234:235], s[24:25], 0, v[132:133]
	s_mov_b32 m0, s39
	s_nop 0
	global_load_lds_dwordx4 v[234:235], off
	s_waitcnt lgkmcnt(8)
	s_barrier
	s_waitcnt lgkmcnt(0)
	s_setprio 1
	s_waitcnt lgkmcnt(0)
	v_mfma_f32_16x16x32_bf16 v[126:129], v[144:147], v[172:175], v[126:129]
	v_mfma_f32_16x16x32_bf16 v[122:125], v[164:167], v[172:175], v[122:125]
	v_mfma_f32_16x16x32_bf16 v[118:121], v[144:147], v[180:183], v[118:121]
	v_mfma_f32_16x16x32_bf16 v[114:117], v[164:167], v[180:183], v[114:117]
	v_mfma_f32_16x16x32_bf16 v[102:105], v[144:147], v[188:191], v[102:105]
	v_mfma_f32_16x16x32_bf16 v[98:101], v[164:167], v[188:191], v[98:101]
	v_mfma_f32_16x16x32_bf16 v[86:89], v[144:147], v[196:199], v[86:89]
	v_mfma_f32_16x16x32_bf16 v[82:85], v[164:167], v[196:199], v[82:85]
	v_mfma_f32_16x16x32_bf16 v[126:129], v[160:163], v[176:179], v[126:129]
	v_mfma_f32_16x16x32_bf16 v[122:125], v[168:171], v[176:179], v[122:125]
	v_mfma_f32_16x16x32_bf16 v[118:121], v[160:163], v[184:187], v[118:121]
	v_mfma_f32_16x16x32_bf16 v[114:117], v[168:171], v[184:187], v[114:117]
	v_mfma_f32_16x16x32_bf16 v[102:105], v[160:163], v[192:195], v[102:105]
	v_mfma_f32_16x16x32_bf16 v[98:101], v[168:171], v[192:195], v[98:101]
	v_mfma_f32_16x16x32_bf16 v[86:89], v[160:163], v[200:203], v[86:89]
	v_mfma_f32_16x16x32_bf16 v[82:85], v[168:171], v[200:203], v[82:85]
	s_setprio 0
	s_barrier
	s_add_i32 s24, 0, 0x1c000
	s_add_i32 s25, s56, s29
	v_add_u32_e32 v159, s24, v141
	v_lshl_add_u64 v[148:149], v[148:149], 0, s[20:21]
	s_mov_b32 m0, s25
	ds_read_b128 v[234:237], v159
	ds_read_b128 v[238:241], v159 offset:1024
	ds_read_b128 v[242:245], v159 offset:2048
	ds_read_b128 v[246:249], v159 offset:3072
	global_load_lds_dwordx4 v[148:149], off
	v_lshl_add_u64 v[148:149], v[204:205], 0, s[20:21]
	s_add_i32 m0, s25, 0x2000
	s_nop 0
	global_load_lds_dwordx4 v[148:149], off
	s_barrier
	s_waitcnt lgkmcnt(0)
	s_setprio 1
	s_waitcnt lgkmcnt(0)
	v_mfma_f32_16x16x32_bf16 v[110:113], v[234:237], v[172:175], v[110:113]
	v_mfma_f32_16x16x32_bf16 v[106:109], v[242:245], v[172:175], v[106:109]
	v_mfma_f32_16x16x32_bf16 v[94:97], v[234:237], v[180:183], v[94:97]
	v_mfma_f32_16x16x32_bf16 v[90:93], v[242:245], v[180:183], v[90:93]
	v_mfma_f32_16x16x32_bf16 v[78:81], v[234:237], v[188:191], v[78:81]
	v_mfma_f32_16x16x32_bf16 v[74:77], v[242:245], v[188:191], v[74:77]
	v_mfma_f32_16x16x32_bf16 v[70:73], v[234:237], v[196:199], v[70:73]
	v_mfma_f32_16x16x32_bf16 v[66:69], v[242:245], v[196:199], v[66:69]
	v_mfma_f32_16x16x32_bf16 v[110:113], v[238:241], v[176:179], v[110:113]
	v_mfma_f32_16x16x32_bf16 v[106:109], v[246:249], v[176:179], v[106:109]
	v_mfma_f32_16x16x32_bf16 v[94:97], v[238:241], v[184:187], v[94:97]
	v_mfma_f32_16x16x32_bf16 v[90:93], v[246:249], v[184:187], v[90:93]
	v_mfma_f32_16x16x32_bf16 v[78:81], v[238:241], v[192:195], v[78:81]
	v_mfma_f32_16x16x32_bf16 v[74:77], v[246:249], v[192:195], v[74:77]
	v_mfma_f32_16x16x32_bf16 v[70:73], v[238:241], v[200:203], v[70:73]
	v_mfma_f32_16x16x32_bf16 v[66:69], v[246:249], v[200:203], v[66:69]
	s_setprio 0
	s_mov_b32 m0, s42
	v_lshl_add_u64 v[148:149], v[250:251], 0, s[20:21]
	s_barrier
	ds_read_b128 v[172:175], v143 offset:49152
	ds_read_b128 v[176:179], v143 offset:50176
	ds_read_b128 v[180:183], v143 offset:51200
	ds_read_b128 v[184:187], v143 offset:52224
	ds_read_b128 v[188:191], v143 offset:53248
	ds_read_b128 v[192:195], v143 offset:54272
	ds_read_b128 v[196:199], v143 offset:55296
	ds_read_b128 v[200:203], v143 offset:56320
	global_load_lds_dwordx4 v[148:149], off
	v_lshl_add_u64 v[148:149], v[252:253], 0, s[20:21]
	s_mov_b32 m0, s43
	s_nop 0
	global_load_lds_dwordx4 v[148:149], off
	s_barrier
	s_waitcnt lgkmcnt(0)
	s_setprio 1
	s_waitcnt lgkmcnt(0)
	v_mfma_f32_16x16x32_bf16 v[62:65], v[144:147], v[172:175], v[62:65]
	v_mfma_f32_16x16x32_bf16 v[58:61], v[164:167], v[172:175], v[58:61]
	v_mfma_f32_16x16x32_bf16 v[54:57], v[144:147], v[180:183], v[54:57]
	v_mfma_f32_16x16x32_bf16 v[50:53], v[164:167], v[180:183], v[50:53]
	v_mfma_f32_16x16x32_bf16 v[38:41], v[144:147], v[188:191], v[38:41]
	v_mfma_f32_16x16x32_bf16 v[34:37], v[164:167], v[188:191], v[34:37]
	v_mfma_f32_16x16x32_bf16 v[22:25], v[144:147], v[196:199], v[22:25]
	v_mfma_f32_16x16x32_bf16 v[18:21], v[164:167], v[196:199], v[18:21]
	v_mfma_f32_16x16x32_bf16 v[62:65], v[160:163], v[176:179], v[62:65]
	v_mfma_f32_16x16x32_bf16 v[58:61], v[168:171], v[176:179], v[58:61]
	v_mfma_f32_16x16x32_bf16 v[54:57], v[160:163], v[184:187], v[54:57]
	v_mfma_f32_16x16x32_bf16 v[50:53], v[168:171], v[184:187], v[50:53]
	v_mfma_f32_16x16x32_bf16 v[38:41], v[160:163], v[192:195], v[38:41]
	v_mfma_f32_16x16x32_bf16 v[34:37], v[168:171], v[192:195], v[34:37]
	v_mfma_f32_16x16x32_bf16 v[22:25], v[160:163], v[200:203], v[22:25]
	v_mfma_f32_16x16x32_bf16 v[18:21], v[168:171], v[200:203], v[18:21]
	s_setprio 0
	s_barrier
	s_add_u32 s22, s22, 0x40080
	s_addc_u32 s23, s23, 0
	s_add_i32 s24, s24, s29
	v_lshl_add_u64 v[144:145], s[22:23], 0, v[0:1]
	s_mov_b32 m0, s24
	s_nop 0
	global_load_lds_dwordx4 v[144:145], off
	v_lshl_add_u64 v[144:145], s[22:23], 0, v[130:131]
	s_add_i32 m0, s24, 0x2000
	s_nop 0
	global_load_lds_dwordx4 v[144:145], off
	s_waitcnt vmcnt(6)
	s_barrier
	s_setprio 1
	v_mfma_f32_16x16x32_bf16 v[46:49], v[234:237], v[172:175], v[46:49]
	v_mfma_f32_16x16x32_bf16 v[42:45], v[242:245], v[172:175], v[42:45]
	v_mfma_f32_16x16x32_bf16 v[30:33], v[234:237], v[180:183], v[30:33]
	v_mfma_f32_16x16x32_bf16 v[26:29], v[242:245], v[180:183], v[26:29]
	v_mfma_f32_16x16x32_bf16 v[14:17], v[234:237], v[188:191], v[14:17]
	v_mfma_f32_16x16x32_bf16 v[10:13], v[242:245], v[188:191], v[10:13]
	v_mfma_f32_16x16x32_bf16 v[6:9], v[234:237], v[196:199], v[6:9]
	v_mfma_f32_16x16x32_bf16 v[2:5], v[242:245], v[196:199], v[2:5]
	v_mfma_f32_16x16x32_bf16 v[46:49], v[238:241], v[176:179], v[46:49]
	v_mfma_f32_16x16x32_bf16 v[42:45], v[246:249], v[176:179], v[42:45]
	v_mfma_f32_16x16x32_bf16 v[30:33], v[238:241], v[184:187], v[30:33]
	v_mfma_f32_16x16x32_bf16 v[26:29], v[246:249], v[184:187], v[26:29]
	v_mfma_f32_16x16x32_bf16 v[14:17], v[238:241], v[192:195], v[14:17]
	v_mfma_f32_16x16x32_bf16 v[10:13], v[246:249], v[192:195], v[10:13]
	v_mfma_f32_16x16x32_bf16 v[6:9], v[238:241], v[200:203], v[6:9]
	v_mfma_f32_16x16x32_bf16 v[2:5], v[246:249], v[200:203], v[2:5]
	s_setprio 0
	s_add_i32 s55, s55, 2
	s_add_u32 s53, s53, 0x100
	s_addc_u32 s54, s54, 0
	s_add_u32 s18, s18, 0x100
	s_addc_u32 s19, s19, 0
	s_cmp_gt_u32 s55, 13
	s_barrier
	s_cbranch_scc0 .LBB0_177
.Lup_epi:
	s_add_u32 s100, s51, 0x40080
	s_addc_u32 s101, s11, 0
	v_lshl_add_u64 v[160:161], s[100:101], 0, v[138:139]
	s_add_i32 m0, s3, 0xc000
	s_nop 0
	global_load_lds_dwordx4 v[160:161], off
	v_lshl_add_u64 v[160:161], s[100:101], 0, v[136:137]
	s_add_i32 m0, s3, 0xe000
	s_nop 0
	global_load_lds_dwordx4 v[160:161], off
	s_mov_b32 s100, 1
	s_mul_hi_i32 s11, s50, 0x2e8ba2e9
	s_lshr_b32 s18, s11, 31
	s_ashr_i32 s11, s11, 1
	s_add_i32 s11, s11, s18
	s_lshl_b32 s9, s50, 8
	s_mul_i32 s18, s11, 0xb580000
	s_mul_hi_i32 s19, s11, 0xb580000
	s_add_u32 s18, s46, s18
	s_mulk_i32 s11, 0xf500
	s_addc_u32 s19, s47, s19
	s_add_i32 s11, s11, s9
	v_or_b32_e32 v144, s11, v142
	v_lshl_add_u32 v148, s2, 8, v140
	v_ashrrev_i32_e32 v145, 31, v144
	v_lshl_add_u64 v[144:145], v[144:145], 1, s[18:19]
	s_movk_i32 s2, 0x1600
	v_cvt_pk_bf16_f32 v70, v70, v71
	v_cvt_pk_bf16_f32 v71, v72, v73
	v_cvt_pk_bf16_f32 v72, v66, v67
	v_add_u32_e32 v66, 0x80, v148
	v_mad_i64_i32 v[146:147], s[18:19], v148, s2, v[144:145]
	v_cvt_pk_bf16_f32 v110, v110, v111
	v_cvt_pk_bf16_f32 v111, v112, v113
	v_cvt_pk_bf16_f32 v112, v106, v107
	v_cvt_pk_bf16_f32 v113, v108, v109
	v_or_b32_e32 v106, 16, v148
	v_mad_i64_i32 v[66:67], s[18:19], v66, s2, v[144:145]
	v_cvt_pk_bf16_f32 v46, v46, v47
	v_cvt_pk_bf16_f32 v47, v48, v49
	v_cvt_pk_bf16_f32 v48, v42, v43
	v_cvt_pk_bf16_f32 v49, v44, v45
	v_add_u32_e32 v42, 0x90, v148
	global_store_dwordx4 v[146:147], v[110:113], off offset:256
	v_cvt_pk_bf16_f32 v94, v94, v95
	v_cvt_pk_bf16_f32 v95, v96, v97
	v_mad_i64_i32 v[110:111], s[18:19], v106, s2, v[144:145]
	v_cvt_pk_bf16_f32 v96, v90, v91
	v_cvt_pk_bf16_f32 v97, v92, v93
	v_or_b32_e32 v90, 32, v148
	global_store_dwordx4 v[66:67], v[46:49], off offset:256
	v_cvt_pk_bf16_f32 v30, v30, v31
	v_cvt_pk_bf16_f32 v31, v32, v33
	v_mad_i64_i32 v[46:47], s[18:19], v42, s2, v[144:145]
	v_cvt_pk_bf16_f32 v32, v26, v27
	v_cvt_pk_bf16_f32 v33, v28, v29
	v_add_u32_e32 v26, 0xa0, v148
	global_store_dwordx4 v[110:111], v[94:97], off offset:256
	v_cvt_pk_bf16_f32 v78, v78, v79
	v_cvt_pk_bf16_f32 v79, v80, v81
	v_mad_i64_i32 v[94:95], s[18:19], v90, s2, v[144:145]
	v_cvt_pk_bf16_f32 v80, v74, v75
	v_cvt_pk_bf16_f32 v81, v76, v77
	v_or_b32_e32 v74, 48, v148
	global_store_dwordx4 v[46:47], v[30:33], off offset:256
	v_cvt_pk_bf16_f32 v14, v14, v15
	v_cvt_pk_bf16_f32 v15, v16, v17
	v_mad_i64_i32 v[30:31], s[18:19], v26, s2, v[144:145]
	v_cvt_pk_bf16_f32 v16, v10, v11
	v_cvt_pk_bf16_f32 v17, v12, v13
	v_add_u32_e32 v10, 0xb0, v148
	global_store_dwordx4 v[94:95], v[78:81], off offset:256
	global_store_dwordx4 v[30:31], v[14:17], off offset:256
	v_cvt_pk_bf16_f32 v126, v126, v127
	v_mad_i64_i32 v[78:79], s[18:19], v74, s2, v[144:145]
	v_mad_i64_i32 v[14:15], s[18:19], v10, s2, v[144:145]
	v_cvt_pk_bf16_f32 v127, v128, v129
	v_cvt_pk_bf16_f32 v128, v122, v123
	v_cvt_pk_bf16_f32 v129, v124, v125
	v_cvt_pk_bf16_f32 v106, v118, v119
	v_cvt_pk_bf16_f32 v107, v120, v121
	v_cvt_pk_bf16_f32 v108, v114, v115
	v_cvt_pk_bf16_f32 v109, v116, v117
	v_cvt_pk_bf16_f32 v90, v102, v103
	v_cvt_pk_bf16_f32 v91, v104, v105
	v_cvt_pk_bf16_f32 v92, v98, v99
	v_cvt_pk_bf16_f32 v93, v100, v101
	v_cvt_pk_bf16_f32 v74, v86, v87
	v_cvt_pk_bf16_f32 v75, v88, v89
	v_cvt_pk_bf16_f32 v76, v82, v83
	v_cvt_pk_bf16_f32 v77, v84, v85
	v_cvt_pk_bf16_f32 v73, v68, v69
	v_cvt_pk_bf16_f32 v62, v62, v63
	v_cvt_pk_bf16_f32 v63, v64, v65
	v_cvt_pk_bf16_f32 v64, v58, v59
	v_cvt_pk_bf16_f32 v65, v60, v61
	v_cvt_pk_bf16_f32 v42, v54, v55
	v_cvt_pk_bf16_f32 v43, v56, v57
	v_cvt_pk_bf16_f32 v44, v50, v51
	v_cvt_pk_bf16_f32 v45, v52, v53
	v_cvt_pk_bf16_f32 v26, v38, v39
	v_cvt_pk_bf16_f32 v27, v40, v41
	v_cvt_pk_bf16_f32 v28, v34, v35
	v_cvt_pk_bf16_f32 v29, v36, v37
	v_cvt_pk_bf16_f32 v10, v22, v23
	v_cvt_pk_bf16_f32 v11, v24, v25
	v_cvt_pk_bf16_f32 v12, v18, v19
	v_cvt_pk_bf16_f32 v13, v20, v21
	v_cvt_pk_bf16_f32 v6, v6, v7
	v_cvt_pk_bf16_f32 v7, v8, v9
	v_cvt_pk_bf16_f32 v8, v2, v3
	v_cvt_pk_bf16_f32 v9, v4, v5
	s_and_b64 vcc, exec, s[40:41]
	s_mov_b32 s50, s8
	s_mov_b32 s2, s10
	s_mov_b64 s[18:19], s[14:15]
	s_mov_b64 s[22:23], s[12:13]
	s_mov_b32 s56, s66
	global_store_dwordx4 v[146:147], v[126:129], off
	global_store_dwordx4 v[110:111], v[106:109], off
	global_store_dwordx4 v[94:95], v[90:93], off
	global_store_dwordx4 v[78:79], v[74:77], off
	global_store_dwordx4 v[78:79], v[70:73], off offset:256
	global_store_dwordx4 v[66:67], v[62:65], off
	global_store_dwordx4 v[46:47], v[42:45], off
	global_store_dwordx4 v[30:31], v[26:29], off
	global_store_dwordx4 v[14:15], v[10:13], off
	global_store_dwordx4 v[14:15], v[6:9], off offset:256
	s_cbranch_vccz .LBB0_174
	s_waitcnt vmcnt(0)
	s_cmpk_gt_u32 s26, 0xff
	s_cbranch_scc1 .LBB0_181
	s_barrier
